# Up GEMM K-loop: per-phase s_setprio flips deleted, one static raise for waves 0-3 before the loop (guide 7.4 step b)
# speedup vs baseline: 1.0042x; 1.0039x over previous
.LBB0_2347:
	s_ashr_i32 s15, s14, 31
	s_lshl_b64 s[16:17], s[14:15], 19
	s_add_u32 s16, s22, s16
	s_addc_u32 s17, s23, s17
	s_and_b64 s[18:19], s[4:5], exec
	s_cselect_b32 s7, s17, s3
	s_cselect_b32 s15, s16, s2
	s_ashr_i32 s13, s12, 31
	s_lshl_b64 s[18:19], s[12:13], 19
	s_add_u32 s18, s24, s18
	s_addc_u32 s19, s25, s19
	s_and_b64 s[46:47], s[4:5], exec
	s_cselect_b32 s13, s19, s1
	s_cselect_b32 s50, s18, s0
	s_add_u32 s46, s2, 0x40080
	s_addc_u32 s47, s3, 0
	s_add_u32 s51, s0, 0x100
	v_mov_b32_e32 v4, 0
	s_addc_u32 s62, s1, 0
	s_mov_b32 s71, -2
	v_mov_b32_e32 v5, v4
	v_mov_b32_e32 v6, v4
	v_mov_b32_e32 v7, v4
	v_mov_b32_e32 v8, v4
	v_mov_b32_e32 v9, v4
	v_mov_b32_e32 v10, v4
	v_mov_b32_e32 v11, v4
	v_mov_b32_e32 v20, v4
	v_mov_b32_e32 v21, v4
	v_mov_b32_e32 v22, v4
	v_mov_b32_e32 v23, v4
	v_mov_b32_e32 v24, v4
	v_mov_b32_e32 v25, v4
	v_mov_b32_e32 v26, v4
	v_mov_b32_e32 v27, v4
	v_mov_b32_e32 v36, v4
	v_mov_b32_e32 v37, v4
	v_mov_b32_e32 v38, v4
	v_mov_b32_e32 v39, v4
	v_mov_b32_e32 v40, v4
	v_mov_b32_e32 v41, v4
	v_mov_b32_e32 v42, v4
	v_mov_b32_e32 v43, v4
	s_waitcnt vmcnt(0)
	v_mov_b32_e32 v52, v4
	v_mov_b32_e32 v53, v4
	v_mov_b32_e32 v54, v4
	v_mov_b32_e32 v55, v4
	v_mov_b32_e32 v56, v4
	v_mov_b32_e32 v57, v4
	v_mov_b32_e32 v58, v4
	v_mov_b32_e32 v59, v4
	v_mov_b32_e32 v12, v4
	v_mov_b32_e32 v13, v4
	v_mov_b32_e32 v14, v4
	v_mov_b32_e32 v15, v4
	v_mov_b32_e32 v16, v4
	v_mov_b32_e32 v17, v4
	v_mov_b32_e32 v18, v4
	v_mov_b32_e32 v19, v4
	v_mov_b32_e32 v28, v4
	v_mov_b32_e32 v29, v4
	v_mov_b32_e32 v30, v4
	v_mov_b32_e32 v31, v4
	v_mov_b32_e32 v32, v4
	v_mov_b32_e32 v33, v4
	v_mov_b32_e32 v34, v4
	v_mov_b32_e32 v35, v4
	v_mov_b32_e32 v44, v4
	v_mov_b32_e32 v45, v4
	v_mov_b32_e32 v46, v4
	v_mov_b32_e32 v47, v4
	v_mov_b32_e32 v48, v4
	v_mov_b32_e32 v49, v4
	v_mov_b32_e32 v50, v4
	v_mov_b32_e32 v51, v4
	v_mov_b32_e32 v60, v4
	v_mov_b32_e32 v61, v4
	v_mov_b32_e32 v62, v4
	v_mov_b32_e32 v63, v4
	v_mov_b32_e32 v64, v4
	v_mov_b32_e32 v65, v4
	v_mov_b32_e32 v66, v4
	v_mov_b32_e32 v67, v4
	v_mov_b32_e32 v68, v4
	v_mov_b32_e32 v69, v4
	v_mov_b32_e32 v70, v4
	v_mov_b32_e32 v71, v4
	v_mov_b32_e32 v72, v4
	v_mov_b32_e32 v73, v4
	v_mov_b32_e32 v74, v4
	v_mov_b32_e32 v75, v4
	v_mov_b32_e32 v84, v4
	v_mov_b32_e32 v85, v4
	v_mov_b32_e32 v86, v4
	v_mov_b32_e32 v87, v4
	v_mov_b32_e32 v88, v4
	v_mov_b32_e32 v89, v4
	v_mov_b32_e32 v90, v4
	v_mov_b32_e32 v91, v4
	v_mov_b32_e32 v100, v4
	v_mov_b32_e32 v101, v4
	v_mov_b32_e32 v102, v4
	v_mov_b32_e32 v103, v4
	v_mov_b32_e32 v104, v4
	v_mov_b32_e32 v105, v4
	v_mov_b32_e32 v106, v4
	v_mov_b32_e32 v107, v4
	v_mov_b32_e32 v116, v4
	v_mov_b32_e32 v117, v4
	v_mov_b32_e32 v118, v4
	v_mov_b32_e32 v119, v4
	v_mov_b32_e32 v120, v4
	v_mov_b32_e32 v121, v4
	v_mov_b32_e32 v122, v4
	v_mov_b32_e32 v123, v4
	v_mov_b32_e32 v76, v4
	v_mov_b32_e32 v77, v4
	v_mov_b32_e32 v78, v4
	v_mov_b32_e32 v79, v4
	v_mov_b32_e32 v80, v4
	v_mov_b32_e32 v81, v4
	v_mov_b32_e32 v82, v4
	v_mov_b32_e32 v83, v4
	v_mov_b32_e32 v92, v4
	v_mov_b32_e32 v93, v4
	v_mov_b32_e32 v94, v4
	v_mov_b32_e32 v95, v4
	v_mov_b32_e32 v96, v4
	v_mov_b32_e32 v97, v4
	v_mov_b32_e32 v98, v4
	v_mov_b32_e32 v99, v4
	v_mov_b32_e32 v108, v4
	v_mov_b32_e32 v109, v4
	v_mov_b32_e32 v110, v4
	v_mov_b32_e32 v111, v4
	v_mov_b32_e32 v112, v4
	v_mov_b32_e32 v113, v4
	v_mov_b32_e32 v114, v4
	v_mov_b32_e32 v115, v4
	v_mov_b32_e32 v124, v4
	v_mov_b32_e32 v125, v4
	v_mov_b32_e32 v126, v4
	v_mov_b32_e32 v127, v4
	v_mov_b32_e32 v128, v4
	v_mov_b32_e32 v129, v4
	v_mov_b32_e32 v130, v4
	v_mov_b32_e32 v131, v4
	v_readlane_b32 s100, v255, 8
	s_cmp_lt_u32 s100, 4
	s_cbranch_scc0 .Lup_noprio
	s_setprio 1
	s_branch .Lup_prio_done
.Lup_noprio:
	s_setprio 0
.Lup_prio_done:
.LBB0_2348:
	s_add_u32 s0, s46, 0xfffc0080
	s_addc_u32 s1, s47, -1
	s_add_i32 s64, 0, 0x10000
	s_cmp_eq_u32 s71, 12
	s_cselect_b32 s3, s7, s1
	s_cselect_b32 s2, s15, s0
	s_cselect_b32 s1, s13, s62
	s_cselect_b32 s0, s50, s51
	s_add_i32 s76, 0, 0x14000
	v_add_u32_e32 v144, s64, v3
	v_add_u32_e32 v167, s76, v3
	ds_read_b128 v[132:135], v144
	ds_read_b128 v[136:139], v144 offset:1024
	ds_read_b128 v[140:143], v144 offset:2048
	ds_read_b128 v[144:147], v144 offset:3072
	ds_read_b128 v[158:161], v167
	ds_read_b128 v[162:165], v167 offset:1024
	ds_read_b128 v[168:171], v167 offset:2048
	ds_read_b128 v[172:175], v167 offset:3072
	v_lshl_add_u64 v[208:209], s[46:47], 0, v[154:155]
	s_add_i32 m0, s21, 0xc000
	ds_read_b128 v[176:179], v166
	ds_read_b128 v[180:183], v166 offset:1024
	ds_read_b128 v[184:187], v166 offset:2048
	ds_read_b128 v[188:191], v166 offset:3072
	ds_read_b128 v[192:195], v166 offset:4096
	ds_read_b128 v[196:199], v166 offset:5120
	ds_read_b128 v[200:203], v166 offset:6144
	ds_read_b128 v[204:207], v166 offset:7168
	global_load_lds_dwordx4 v[208:209], off
	v_lshl_add_u64 v[208:209], s[46:47], 0, v[156:157]
	s_add_i32 m0, s21, 0xe000
	s_nop 0
	global_load_lds_dwordx4 v[208:209], off
	s_waitcnt vmcnt(8)
	s_waitcnt lgkmcnt(0)
	s_barrier
	s_waitcnt lgkmcnt(0)
	v_mfma_f32_16x16x32_bf16 v[128:131], v[132:135], v[176:179], v[128:131]
	v_mfma_f32_16x16x32_bf16 v[124:127], v[140:143], v[176:179], v[124:127]
	v_mfma_f32_16x16x32_bf16 v[112:115], v[132:135], v[184:187], v[112:115]
	v_mfma_f32_16x16x32_bf16 v[108:111], v[140:143], v[184:187], v[108:111]
	v_mfma_f32_16x16x32_bf16 v[96:99], v[132:135], v[192:195], v[96:99]
	v_mfma_f32_16x16x32_bf16 v[92:95], v[140:143], v[192:195], v[92:95]
	v_mfma_f32_16x16x32_bf16 v[80:83], v[132:135], v[200:203], v[80:83]
	v_mfma_f32_16x16x32_bf16 v[76:79], v[140:143], v[200:203], v[76:79]
	v_mfma_f32_16x16x32_bf16 v[128:131], v[136:139], v[180:183], v[128:131]
	v_mfma_f32_16x16x32_bf16 v[124:127], v[144:147], v[180:183], v[124:127]
	v_mfma_f32_16x16x32_bf16 v[112:115], v[136:139], v[188:191], v[112:115]
	v_mfma_f32_16x16x32_bf16 v[108:111], v[144:147], v[188:191], v[108:111]
	v_mfma_f32_16x16x32_bf16 v[96:99], v[136:139], v[196:199], v[96:99]
	v_mfma_f32_16x16x32_bf16 v[92:95], v[144:147], v[196:199], v[92:95]
	v_mfma_f32_16x16x32_bf16 v[80:83], v[136:139], v[204:207], v[80:83]
	v_mfma_f32_16x16x32_bf16 v[76:79], v[144:147], v[204:207], v[76:79]
	v_mfma_f32_16x16x32_bf16 v[120:123], v[158:161], v[176:179], v[120:123]
	v_mfma_f32_16x16x32_bf16 v[116:119], v[168:171], v[176:179], v[116:119]
	v_mfma_f32_16x16x32_bf16 v[104:107], v[158:161], v[184:187], v[104:107]
	v_mfma_f32_16x16x32_bf16 v[100:103], v[168:171], v[184:187], v[100:103]
	v_mfma_f32_16x16x32_bf16 v[88:91], v[158:161], v[192:195], v[88:91]
	v_mfma_f32_16x16x32_bf16 v[84:87], v[168:171], v[192:195], v[84:87]
	v_mfma_f32_16x16x32_bf16 v[72:75], v[158:161], v[200:203], v[72:75]
	v_mfma_f32_16x16x32_bf16 v[68:71], v[168:171], v[200:203], v[68:71]
	v_mfma_f32_16x16x32_bf16 v[120:123], v[162:165], v[180:183], v[120:123]
	v_mfma_f32_16x16x32_bf16 v[116:119], v[172:175], v[180:183], v[116:119]
	v_mfma_f32_16x16x32_bf16 v[104:107], v[162:165], v[188:191], v[104:107]
	v_mfma_f32_16x16x32_bf16 v[100:103], v[172:175], v[188:191], v[100:103]
	v_mfma_f32_16x16x32_bf16 v[88:91], v[162:165], v[196:199], v[88:91]
	v_mfma_f32_16x16x32_bf16 v[84:87], v[172:175], v[196:199], v[84:87]
	v_mfma_f32_16x16x32_bf16 v[72:75], v[162:165], v[204:207], v[72:75]
	v_mfma_f32_16x16x32_bf16 v[68:71], v[172:175], v[204:207], v[68:71]
	s_barrier
	s_add_i32 s64, s64, s29
	v_lshl_add_u64 v[208:209], s[0:1], 0, v[148:149]
	s_mov_b32 m0, s64
	ds_read_b128 v[176:179], v166 offset:16384
	ds_read_b128 v[180:183], v166 offset:17408
	ds_read_b128 v[184:187], v166 offset:18432
	ds_read_b128 v[188:191], v166 offset:19456
	ds_read_b128 v[192:195], v166 offset:20480
	ds_read_b128 v[196:199], v166 offset:21504
	ds_read_b128 v[200:203], v166 offset:22528
	ds_read_b128 v[204:207], v166 offset:23552
	global_load_lds_dwordx4 v[208:209], off
	s_add_i32 m0, s64, 0x2000
	s_add_u32 s64, s0, 0x4000
	v_lshl_add_u64 v[210:211], s[0:1], 0, v[152:153]
	s_addc_u32 s65, s1, 0
	s_add_i32 s76, s76, s29
	global_load_lds_dwordx4 v[210:211], off
	v_lshl_add_u64 v[212:213], s[64:65], 0, v[148:149]
	s_mov_b32 m0, s76
	v_lshl_add_u64 v[214:215], s[2:3], 0, v[150:151]
	global_load_lds_dwordx4 v[212:213], off
	v_lshl_add_u64 v[212:213], s[64:65], 0, v[152:153]
	s_add_i32 m0, s76, 0x2000
	s_nop 0
	global_load_lds_dwordx4 v[212:213], off
	v_lshl_add_u64 v[212:213], s[2:3], 0, v[0:1]
	s_mov_b32 m0, s21
	s_nop 0
	global_load_lds_dwordx4 v[212:213], off
	s_mov_b32 m0, s30
	s_nop 0
	global_load_lds_dwordx4 v[214:215], off
	s_waitcnt vmcnt(8)
	s_waitcnt lgkmcnt(0)
	s_barrier
	s_waitcnt lgkmcnt(0)
	v_mfma_f32_16x16x32_bf16 v[64:67], v[132:135], v[176:179], v[64:67]
	v_mfma_f32_16x16x32_bf16 v[60:63], v[140:143], v[176:179], v[60:63]
	v_mfma_f32_16x16x32_bf16 v[48:51], v[132:135], v[184:187], v[48:51]
	v_mfma_f32_16x16x32_bf16 v[44:47], v[140:143], v[184:187], v[44:47]
	v_mfma_f32_16x16x32_bf16 v[32:35], v[132:135], v[192:195], v[32:35]
	v_mfma_f32_16x16x32_bf16 v[28:31], v[140:143], v[192:195], v[28:31]
	v_mfma_f32_16x16x32_bf16 v[16:19], v[132:135], v[200:203], v[16:19]
	v_mfma_f32_16x16x32_bf16 v[12:15], v[140:143], v[200:203], v[12:15]
	v_mfma_f32_16x16x32_bf16 v[64:67], v[136:139], v[180:183], v[64:67]
	v_mfma_f32_16x16x32_bf16 v[60:63], v[144:147], v[180:183], v[60:63]
	v_mfma_f32_16x16x32_bf16 v[48:51], v[136:139], v[188:191], v[48:51]
	v_mfma_f32_16x16x32_bf16 v[44:47], v[144:147], v[188:191], v[44:47]
	v_mfma_f32_16x16x32_bf16 v[32:35], v[136:139], v[196:199], v[32:35]
	v_mfma_f32_16x16x32_bf16 v[28:31], v[144:147], v[196:199], v[28:31]
	v_mfma_f32_16x16x32_bf16 v[16:19], v[136:139], v[204:207], v[16:19]
	v_mfma_f32_16x16x32_bf16 v[12:15], v[144:147], v[204:207], v[12:15]
	v_mfma_f32_16x16x32_bf16 v[56:59], v[158:161], v[176:179], v[56:59]
	v_mfma_f32_16x16x32_bf16 v[52:55], v[168:171], v[176:179], v[52:55]
	v_mfma_f32_16x16x32_bf16 v[40:43], v[158:161], v[184:187], v[40:43]
	v_mfma_f32_16x16x32_bf16 v[36:39], v[168:171], v[184:187], v[36:39]
	v_mfma_f32_16x16x32_bf16 v[24:27], v[158:161], v[192:195], v[24:27]
	v_mfma_f32_16x16x32_bf16 v[20:23], v[168:171], v[192:195], v[20:23]
	v_mfma_f32_16x16x32_bf16 v[8:11], v[158:161], v[200:203], v[8:11]
	v_mfma_f32_16x16x32_bf16 v[4:7], v[168:171], v[200:203], v[4:7]
	v_mfma_f32_16x16x32_bf16 v[56:59], v[162:165], v[180:183], v[56:59]
	v_mfma_f32_16x16x32_bf16 v[52:55], v[172:175], v[180:183], v[52:55]
	v_mfma_f32_16x16x32_bf16 v[40:43], v[162:165], v[188:191], v[40:43]
	v_mfma_f32_16x16x32_bf16 v[36:39], v[172:175], v[188:191], v[36:39]
	v_mfma_f32_16x16x32_bf16 v[24:27], v[162:165], v[196:199], v[24:27]
	v_mfma_f32_16x16x32_bf16 v[20:23], v[172:175], v[196:199], v[20:23]
	v_mfma_f32_16x16x32_bf16 v[8:11], v[162:165], v[204:207], v[8:11]
	v_mfma_f32_16x16x32_bf16 v[4:7], v[172:175], v[204:207], v[4:7]
	s_barrier
	s_add_i32 s64, 0, 0x18000
	s_add_i32 s65, 0, 0x1c000
	v_add_u32_e32 v144, s64, v3
	v_add_u32_e32 v167, s65, v3
	ds_read_b128 v[132:135], v144
	ds_read_b128 v[136:139], v144 offset:1024
	ds_read_b128 v[140:143], v144 offset:2048
	ds_read_b128 v[144:147], v144 offset:3072
	ds_read_b128 v[158:161], v167
	ds_read_b128 v[162:165], v167 offset:1024
	ds_read_b128 v[168:171], v167 offset:2048
	ds_read_b128 v[172:175], v167 offset:3072
	s_add_u32 s2, s2, 0x40000
	s_addc_u32 s3, s3, 0
	s_mov_b32 m0, s31
	v_lshl_add_u64 v[216:217], s[2:3], 0, v[0:1]
	ds_read_b128 v[176:179], v166 offset:32768
	ds_read_b128 v[180:183], v166 offset:33792
	ds_read_b128 v[184:187], v166 offset:34816
	ds_read_b128 v[188:191], v166 offset:35840
	ds_read_b128 v[192:195], v166 offset:36864
	ds_read_b128 v[196:199], v166 offset:37888
	ds_read_b128 v[200:203], v166 offset:38912
	ds_read_b128 v[204:207], v166 offset:39936
	global_load_lds_dwordx4 v[216:217], off
	v_lshl_add_u64 v[216:217], s[2:3], 0, v[150:151]
	s_mov_b32 m0, s52
	s_nop 0
	global_load_lds_dwordx4 v[216:217], off
	s_waitcnt vmcnt(8)
	s_waitcnt lgkmcnt(0)
	s_barrier
	s_waitcnt lgkmcnt(0)
	v_mfma_f32_16x16x32_bf16 v[128:131], v[132:135], v[176:179], v[128:131]
	v_mfma_f32_16x16x32_bf16 v[124:127], v[140:143], v[176:179], v[124:127]
	v_mfma_f32_16x16x32_bf16 v[112:115], v[132:135], v[184:187], v[112:115]
	v_mfma_f32_16x16x32_bf16 v[108:111], v[140:143], v[184:187], v[108:111]
	v_mfma_f32_16x16x32_bf16 v[96:99], v[132:135], v[192:195], v[96:99]
	v_mfma_f32_16x16x32_bf16 v[92:95], v[140:143], v[192:195], v[92:95]
	v_mfma_f32_16x16x32_bf16 v[80:83], v[132:135], v[200:203], v[80:83]
	v_mfma_f32_16x16x32_bf16 v[76:79], v[140:143], v[200:203], v[76:79]
	v_mfma_f32_16x16x32_bf16 v[128:131], v[136:139], v[180:183], v[128:131]
	v_mfma_f32_16x16x32_bf16 v[124:127], v[144:147], v[180:183], v[124:127]
	v_mfma_f32_16x16x32_bf16 v[112:115], v[136:139], v[188:191], v[112:115]
	v_mfma_f32_16x16x32_bf16 v[108:111], v[144:147], v[188:191], v[108:111]
	v_mfma_f32_16x16x32_bf16 v[96:99], v[136:139], v[196:199], v[96:99]
	v_mfma_f32_16x16x32_bf16 v[92:95], v[144:147], v[196:199], v[92:95]
	v_mfma_f32_16x16x32_bf16 v[80:83], v[136:139], v[204:207], v[80:83]
	v_mfma_f32_16x16x32_bf16 v[76:79], v[144:147], v[204:207], v[76:79]
	v_mfma_f32_16x16x32_bf16 v[120:123], v[158:161], v[176:179], v[120:123]
	v_mfma_f32_16x16x32_bf16 v[116:119], v[168:171], v[176:179], v[116:119]
	v_mfma_f32_16x16x32_bf16 v[104:107], v[158:161], v[184:187], v[104:107]
	v_mfma_f32_16x16x32_bf16 v[100:103], v[168:171], v[184:187], v[100:103]
	v_mfma_f32_16x16x32_bf16 v[88:91], v[158:161], v[192:195], v[88:91]
	v_mfma_f32_16x16x32_bf16 v[84:87], v[168:171], v[192:195], v[84:87]
	v_mfma_f32_16x16x32_bf16 v[72:75], v[158:161], v[200:203], v[72:75]
	v_mfma_f32_16x16x32_bf16 v[68:71], v[168:171], v[200:203], v[68:71]
	v_mfma_f32_16x16x32_bf16 v[120:123], v[162:165], v[180:183], v[120:123]
	v_mfma_f32_16x16x32_bf16 v[116:119], v[172:175], v[180:183], v[116:119]
	v_mfma_f32_16x16x32_bf16 v[104:107], v[162:165], v[188:191], v[104:107]
	v_mfma_f32_16x16x32_bf16 v[100:103], v[172:175], v[188:191], v[100:103]
	v_mfma_f32_16x16x32_bf16 v[88:91], v[162:165], v[196:199], v[88:91]
	v_mfma_f32_16x16x32_bf16 v[84:87], v[172:175], v[196:199], v[84:87]
	v_mfma_f32_16x16x32_bf16 v[72:75], v[162:165], v[204:207], v[72:75]
	v_mfma_f32_16x16x32_bf16 v[68:71], v[172:175], v[204:207], v[68:71]
	s_barrier
	s_add_i32 s2, s64, s29
	v_lshl_add_u64 v[208:209], v[208:209], 0, s[60:61]
	s_mov_b32 m0, s2
	ds_read_b128 v[176:179], v166 offset:49152
	ds_read_b128 v[180:183], v166 offset:50176
	ds_read_b128 v[184:187], v166 offset:51200
	ds_read_b128 v[188:191], v166 offset:52224
	ds_read_b128 v[192:195], v166 offset:53248
	ds_read_b128 v[196:199], v166 offset:54272
	ds_read_b128 v[200:203], v166 offset:55296
	ds_read_b128 v[204:207], v166 offset:56320
	global_load_lds_dwordx4 v[208:209], off
	s_add_i32 m0, s2, 0x2000
	s_add_u32 s0, s0, 0x4080
	v_lshl_add_u64 v[208:209], v[210:211], 0, s[60:61]
	s_addc_u32 s1, s1, 0
	s_add_i32 s2, s65, s29
	global_load_lds_dwordx4 v[208:209], off
	v_lshl_add_u64 v[208:209], s[0:1], 0, v[148:149]
	s_mov_b32 m0, s2
	s_nop 0
	global_load_lds_dwordx4 v[208:209], off
	v_lshl_add_u64 v[208:209], s[0:1], 0, v[152:153]
	s_add_i32 m0, s2, 0x2000
	s_nop 0
	global_load_lds_dwordx4 v[208:209], off
	v_lshl_add_u64 v[208:209], v[212:213], 0, s[60:61]
	s_mov_b32 m0, s56
	s_nop 0
	global_load_lds_dwordx4 v[208:209], off
	v_lshl_add_u64 v[208:209], v[214:215], 0, s[60:61]
	s_mov_b32 m0, s57
	s_nop 0
	global_load_lds_dwordx4 v[208:209], off
	s_waitcnt vmcnt(8)
	s_waitcnt lgkmcnt(0)
	s_barrier
	s_waitcnt lgkmcnt(0)
	v_mfma_f32_16x16x32_bf16 v[64:67], v[132:135], v[176:179], v[64:67]
	v_mfma_f32_16x16x32_bf16 v[60:63], v[140:143], v[176:179], v[60:63]
	v_mfma_f32_16x16x32_bf16 v[48:51], v[132:135], v[184:187], v[48:51]
	v_mfma_f32_16x16x32_bf16 v[44:47], v[140:143], v[184:187], v[44:47]
	v_mfma_f32_16x16x32_bf16 v[32:35], v[132:135], v[192:195], v[32:35]
	v_mfma_f32_16x16x32_bf16 v[28:31], v[140:143], v[192:195], v[28:31]
	v_mfma_f32_16x16x32_bf16 v[16:19], v[132:135], v[200:203], v[16:19]
	v_mfma_f32_16x16x32_bf16 v[12:15], v[140:143], v[200:203], v[12:15]
	v_mfma_f32_16x16x32_bf16 v[64:67], v[136:139], v[180:183], v[64:67]
	v_mfma_f32_16x16x32_bf16 v[60:63], v[144:147], v[180:183], v[60:63]
	v_mfma_f32_16x16x32_bf16 v[48:51], v[136:139], v[188:191], v[48:51]
	v_mfma_f32_16x16x32_bf16 v[44:47], v[144:147], v[188:191], v[44:47]
	v_mfma_f32_16x16x32_bf16 v[32:35], v[136:139], v[196:199], v[32:35]
	v_mfma_f32_16x16x32_bf16 v[28:31], v[144:147], v[196:199], v[28:31]
	v_mfma_f32_16x16x32_bf16 v[16:19], v[136:139], v[204:207], v[16:19]
	v_mfma_f32_16x16x32_bf16 v[12:15], v[144:147], v[204:207], v[12:15]
	v_mfma_f32_16x16x32_bf16 v[56:59], v[158:161], v[176:179], v[56:59]
	v_mfma_f32_16x16x32_bf16 v[52:55], v[168:171], v[176:179], v[52:55]
	v_mfma_f32_16x16x32_bf16 v[40:43], v[158:161], v[184:187], v[40:43]
	v_mfma_f32_16x16x32_bf16 v[36:39], v[168:171], v[184:187], v[36:39]
	v_mfma_f32_16x16x32_bf16 v[24:27], v[158:161], v[192:195], v[24:27]
	v_mfma_f32_16x16x32_bf16 v[20:23], v[168:171], v[192:195], v[20:23]
	v_mfma_f32_16x16x32_bf16 v[8:11], v[158:161], v[200:203], v[8:11]
	v_mfma_f32_16x16x32_bf16 v[4:7], v[168:171], v[200:203], v[4:7]
	v_mfma_f32_16x16x32_bf16 v[56:59], v[162:165], v[180:183], v[56:59]
	v_mfma_f32_16x16x32_bf16 v[52:55], v[172:175], v[180:183], v[52:55]
	v_mfma_f32_16x16x32_bf16 v[40:43], v[162:165], v[188:191], v[40:43]
	v_mfma_f32_16x16x32_bf16 v[36:39], v[172:175], v[188:191], v[36:39]
	v_mfma_f32_16x16x32_bf16 v[24:27], v[162:165], v[196:199], v[24:27]
	v_mfma_f32_16x16x32_bf16 v[20:23], v[172:175], v[196:199], v[20:23]
	v_mfma_f32_16x16x32_bf16 v[8:11], v[162:165], v[204:207], v[8:11]
	v_mfma_f32_16x16x32_bf16 v[4:7], v[172:175], v[204:207], v[4:7]
	s_barrier
	s_add_i32 s71, s71, 2
	s_add_u32 s46, s46, 0x100
	s_addc_u32 s47, s47, 0
	s_add_u32 s51, s51, 0x100
	s_addc_u32 s62, s62, 0
	s_cmp_gt_u32 s71, 13
	s_cbranch_scc0 .LBB0_2348
	s_and_b64 vcc, exec, s[10:11]
	s_cbranch_vccz .LBB0_2351
	s_barrier
